# mixer recurrence: next-chunk K/V loads issued before and Q loads in the middle of a re-ordered MFMA section with pipelined LDS reads; GEMM first-iteration waits relaxed
# speedup vs baseline: 1.0019x; 1.0019x over previous
; #define LAS __attribute__((address_space(3)))
; __device__ __forceinline__ f32x4 mfma16(bf16x8 a, bf16x8 b, f32x4 c) { return __builtin_amdgcn_mfma_f32_16x16x32_bf16(a, b, c, 0, 0, 0); }
; __device__ __forceinline__ void mixer_phase(LAS unsigned char* lds, const bf16_t* __restrict__ QKc, const bf16_t* __restrict__ PROJ, bf16_t* HOUT, const float* __restrict__ DEN, const float* __restrict__ GS, int vcu, int G) {
;     ...
;             const float dec = vb[512];
; #pragma unroll
;             for (int p = 0; p < 2; ++p)
; #pragma unroll
;                 for (int et = 0; et < 3; ++et) accC[p][et] = accC[p][et] * dec;
;             f32x4 accO[3];
; #pragma unroll
;             for (int et = 0; et < 3; ++et) accO[et] = (f32x4){0.f, 0.f, 0.f, 0.f};
; #pragma unroll
;             for (int p = 0; p < 2; ++p) {
;                 const int KSB = p ? MX_KS1 : MX_KS0;
; #pragma unroll
;                 for (int ks = 0; ks < 4; ++ks)
; #pragma unroll
;                     for (int et = 0; et < 3; ++et) { const bf16x8 a = *(const LAS bf16x8*)(lds + MX_CT + (16 * et + l15) * 528 + (128 * p + 32 * ks + 8 * quad) * 2); accO[et] = mfma16(a, qf[4 * p + ks], accO[et]); }
; #pragma unroll
;                 for (int k4 = 0; k4 < 4; ++k4) {
;                     const bf16x8 a = *(const LAS bf16x8*)(lds + KSB + (16 * w + l15) * 272 + (((4 * k4 + quad) ^ ((2 * w + (l15 >> 3)) & 15)) * 16));
; #pragma unroll
;                     for (int et = 0; et < 3; ++et) { const bf16x8 bb = *(const LAS bf16x8*)(lds + MX_VTW + (16 * et + l15) * 272 + (32 * k4 + 8 * quad) * 2); accC[p][et] = mfma16(a, bb, accC[p][et]); }
;                 }
;             }
;             if (c < 31) { MX_LOAD(c + 1); MX_SB_CALC(c + 1); }
.LBB0_524:
	s_or_b64 exec, exec, s[0:1]
	v_mov_b32_e32 v52, s51
	ds_read_b32 v60, v52 offset:2048
	ds_read_b128 v[220:223], v195
	ds_read_b128 v[224:227], v195 offset:8448
	ds_read_b128 v[228:231], v195 offset:16896
	ds_read_b128 v[232:235], v196
	ds_read_b128 v[236:239], v196 offset:8448
	ds_read_b128 v[240:243], v196 offset:16896
	ds_read_b128 v[248:251], v197
	s_waitcnt lgkmcnt(7)
	v_pk_mul_f32 v[46:47], v[46:47], v[60:61] op_sel_hi:[1,0]
	v_pk_mul_f32 v[44:45], v[44:45], v[60:61] op_sel_hi:[1,0]
	v_pk_mul_f32 v[42:43], v[42:43], v[60:61] op_sel_hi:[1,0]
	v_mul_f32_e64 v40, v40, v60
	v_mul_f32_e64 v41, v41, v60
	v_pk_mul_f32 v[38:39], v[38:39], v[60:61] op_sel_hi:[1,0]
	v_pk_mul_f32 v[36:37], v[36:37], v[60:61] op_sel_hi:[1,0]
	v_mul_f32_e64 v94, v94, v60
	v_mul_f32_e64 v95, v95, v60
	v_pk_mul_f32 v[92:93], v[92:93], v[60:61] op_sel_hi:[1,0]
	v_pk_mul_f32 v[90:91], v[90:91], v[60:61] op_sel_hi:[1,0]
	v_pk_mul_f32 v[88:89], v[88:89], v[60:61] op_sel_hi:[1,0]
	v_pk_mul_f32 v[82:83], v[82:83], v[60:61] op_sel_hi:[1,0]
	v_pk_mul_f32 v[80:81], v[80:81], v[60:61] op_sel_hi:[1,0]
	s_mov_b32 s0, 0x100000
	v_lshl_add_u64 v[76:77], v[152:153], 0, s[30:31]
	v_lshl_add_u64 v[106:107], v[150:151], 0, s[30:31]
	v_add_co_u32_e32 v52, vcc, s0, v76
	s_mov_b32 s0, 0x102000
	s_nop 1
	v_addc_co_u32_e32 v53, vcc, 0, v77, vcc
	v_add_co_u32_e32 v60, vcc, s0, v76
	s_mov_b32 s0, 0x104000
	s_nop 1
	v_addc_co_u32_e32 v61, vcc, 0, v77, vcc
	v_add_co_u32_e32 v68, vcc, s0, v76
	s_mov_b32 s0, 0x106000
	s_nop 1
	v_addc_co_u32_e32 v69, vcc, 0, v77, vcc
	v_add_co_u32_e32 v76, vcc, s0, v76
	s_nop 1
	v_addc_co_u32_e32 v77, vcc, 0, v77, vcc
	v_add_co_u32_e32 v210, vcc, s77, v106
	s_nop 1
	v_addc_co_u32_e32 v211, vcc, 0, v107, vcc
	global_load_dwordx4 v[56:59], v[52:53], off offset:2048
	s_nop 0
	global_load_dwordx4 v[52:55], v[52:53], off offset:2304
	s_nop 0
	global_load_dwordx4 v[64:67], v[60:61], off offset:2048
	s_nop 0
	global_load_dwordx4 v[60:63], v[60:61], off offset:2304
	s_nop 0
	global_load_dwordx4 v[72:75], v[68:69], off offset:2048
	s_nop 0
	global_load_dwordx4 v[68:71], v[68:69], off offset:2304
	s_nop 0
	global_load_dwordx4 v[84:87], v[76:77], off offset:2048
	s_nop 0
	global_load_dwordx4 v[76:79], v[76:77], off offset:2304
	s_nop 0
	global_load_dword v105, v[210:211], off
	v_add_co_u32_e32 v210, vcc, 0x11284000, v106
	s_nop 1
	v_addc_co_u32_e32 v211, vcc, 0, v107, vcc
	global_load_dword v209, v[210:211], off
	v_add_co_u32_e32 v210, vcc, 0x11288000, v106
	s_nop 1
	v_addc_co_u32_e32 v211, vcc, 0, v107, vcc
	v_add_co_u32_e32 v106, vcc, 0x1128c000, v106
	global_load_dword v210, v[210:211], off
	s_nop 0
	v_addc_co_u32_e32 v107, vcc, 0, v107, vcc
	global_load_dword v211, v[106:107], off
	s_waitcnt lgkmcnt(6)
	v_mfma_f32_16x16x32_bf16 v[100:103], v[220:223], v[32:35], 0
	ds_read_b128 v[220:223], v197 offset:8448
	s_waitcnt lgkmcnt(6)
	v_mfma_f32_16x16x32_bf16 v[96:99], v[224:227], v[32:35], 0
	ds_read_b128 v[224:227], v197 offset:16896
	s_waitcnt lgkmcnt(6)
	v_mfma_f32_16x16x32_bf16 v[252:255], v[228:231], v[32:35], 0
	ds_read_b128 v[228:231], v198
	s_waitcnt lgkmcnt(6)
	v_mfma_f32_16x16x32_bf16 v[100:103], v[232:235], v[28:31], v[100:103]
	ds_read_b128 v[232:235], v198 offset:8448
	s_waitcnt lgkmcnt(6)
	v_mfma_f32_16x16x32_bf16 v[96:99], v[236:239], v[28:31], v[96:99]
	ds_read_b128 v[236:239], v198 offset:16896
	s_waitcnt lgkmcnt(6)
	v_mfma_f32_16x16x32_bf16 v[252:255], v[240:243], v[28:31], v[252:255]
	ds_read_b128 v[240:243], v199
	s_waitcnt lgkmcnt(6)
	v_mfma_f32_16x16x32_bf16 v[100:103], v[248:251], v[24:27], v[100:103]
	ds_read_b128 v[248:251], v199 offset:8448
	s_waitcnt lgkmcnt(6)
	v_mfma_f32_16x16x32_bf16 v[96:99], v[220:223], v[24:27], v[96:99]
	ds_read_b128 v[220:223], v199 offset:16896
	s_waitcnt lgkmcnt(6)
	v_mfma_f32_16x16x32_bf16 v[252:255], v[224:227], v[24:27], v[252:255]
	ds_read_b128 v[224:227], v200
	s_waitcnt lgkmcnt(6)
	v_mfma_f32_16x16x32_bf16 v[100:103], v[228:231], v[20:23], v[100:103]
	ds_read_b128 v[228:231], v200 offset:8448
	s_waitcnt lgkmcnt(6)
	v_mfma_f32_16x16x32_bf16 v[96:99], v[232:235], v[20:23], v[96:99]
	ds_read_b128 v[232:235], v200 offset:16896
	s_waitcnt lgkmcnt(6)
	v_mfma_f32_16x16x32_bf16 v[252:255], v[236:239], v[20:23], v[252:255]
	ds_read_b128 v[236:239], v201
	s_waitcnt lgkmcnt(6)
	v_mfma_f32_16x16x32_bf16 v[100:103], v[240:243], v[16:19], v[100:103]
	ds_read_b128 v[240:243], v201 offset:8448
	s_waitcnt lgkmcnt(6)
	v_mfma_f32_16x16x32_bf16 v[96:99], v[248:251], v[16:19], v[96:99]
	ds_read_b128 v[248:251], v201 offset:16896
	s_waitcnt lgkmcnt(6)
	v_mfma_f32_16x16x32_bf16 v[252:255], v[220:223], v[16:19], v[252:255]
	ds_read_b128 v[220:223], v202
	s_waitcnt lgkmcnt(6)
	v_mfma_f32_16x16x32_bf16 v[100:103], v[224:227], v[12:15], v[100:103]
	ds_read_b128 v[224:227], v202 offset:8448
	s_waitcnt lgkmcnt(6)
	v_mfma_f32_16x16x32_bf16 v[96:99], v[228:231], v[12:15], v[96:99]
	ds_read_b128 v[228:231], v202 offset:16896
	s_waitcnt lgkmcnt(6)
	v_mfma_f32_16x16x32_bf16 v[252:255], v[232:235], v[12:15], v[252:255]
	ds_read_b128 v[232:235], v184
	s_waitcnt lgkmcnt(6)
	v_mfma_f32_16x16x32_bf16 v[100:103], v[236:239], v[8:11], v[100:103]
	ds_read_b128 v[236:239], v185
	s_waitcnt lgkmcnt(6)
	v_mfma_f32_16x16x32_bf16 v[96:99], v[240:243], v[8:11], v[96:99]
	ds_read_b128 v[240:243], v185 offset:4352
	s_waitcnt lgkmcnt(6)
; #define LAS __attribute__((address_space(3)))
; __device__ __forceinline__ f32x4 mfma16(bf16x8 a, bf16x8 b, f32x4 c) { return __builtin_amdgcn_mfma_f32_16x16x32_bf16(a, b, c, 0, 0, 0); }
; __device__ __forceinline__ void mixer_phase(LAS unsigned char* lds, const bf16_t* __restrict__ QKc, const bf16_t* __restrict__ PROJ, bf16_t* HOUT, const float* __restrict__ DEN, const float* __restrict__ GS, int vcu, int G) {
;     ...
;         float sb_b = 0.f, sb_u = 0.f, sb_pm = 0.f, sb_pmall = 0.f;
;     ...
; #pragma unroll
;             for (int p = 0; p < 2; ++p) {
;                 const int KSB = p ? MX_KS1 : MX_KS0;
; #pragma unroll
;                 for (int ks = 0; ks < 4; ++ks)
; #pragma unroll
;                     for (int et = 0; et < 3; ++et) { const bf16x8 a = *(const LAS bf16x8*)(lds + MX_CT + (16 * et + l15) * 528 + (128 * p + 32 * ks + 8 * quad) * 2); accO[et] = mfma16(a, qf[4 * p + ks], accO[et]); }
; #pragma unroll
;                 for (int k4 = 0; k4 < 4; ++k4) {
;                     const bf16x8 a = *(const LAS bf16x8*)(lds + KSB + (16 * w + l15) * 272 + (((4 * k4 + quad) ^ ((2 * w + (l15 >> 3)) & 15)) * 16));
; #pragma unroll
;                     for (int et = 0; et < 3; ++et) { const bf16x8 bb = *(const LAS bf16x8*)(lds + MX_VTW + (16 * et + l15) * 272 + (32 * k4 + 8 * quad) * 2); accC[p][et] = mfma16(a, bb, accC[p][et]); }
;                 }
;             }
;             if (c < 31) { MX_LOAD(c + 1); MX_SB_CALC(c + 1); }
	v_mfma_f32_16x16x32_bf16 v[252:255], v[248:251], v[8:11], v[252:255]
	ds_read_b128 v[248:251], v185 offset:8704
	s_waitcnt lgkmcnt(6)
	v_mfma_f32_16x16x32_bf16 v[100:103], v[220:223], v[4:7], v[100:103]
	ds_read_b128 v[220:223], v186
	s_waitcnt lgkmcnt(6)
	v_mfma_f32_16x16x32_bf16 v[96:99], v[224:227], v[4:7], v[96:99]
	ds_read_b128 v[224:227], v185 offset:64
	s_waitcnt lgkmcnt(6)
	v_mfma_f32_16x16x32_bf16 v[252:255], v[228:231], v[4:7], v[252:255]
	v_lshl_add_u64 v[4:5], v[154:155], 0, s[30:31]
	global_load_dwordx4 v[32:35], v[4:5], off offset:-256
	global_load_dwordx4 v[28:31], v[4:5], off offset:-192
	global_load_dwordx4 v[24:27], v[4:5], off offset:-128
	global_load_dwordx4 v[20:23], v[4:5], off offset:-64
	global_load_dwordx4 v[16:19], v[4:5], off
	global_load_dwordx4 v[12:15], v[4:5], off offset:64
	global_load_dwordx4 v[8:11], v[4:5], off offset:128
	s_nop 0
	global_load_dwordx4 v[4:7], v[4:5], off offset:192
	ds_read_b128 v[228:231], v185 offset:4416
	s_waitcnt lgkmcnt(5)
	v_mfma_f32_16x16x32_bf16 v[44:47], v[232:235], v[236:239], v[44:47]
	s_waitcnt lgkmcnt(4)
	v_mfma_f32_16x16x32_bf16 v[40:43], v[232:235], v[240:243], v[40:43]
	s_waitcnt lgkmcnt(3)
	v_mfma_f32_16x16x32_bf16 v[36:39], v[232:235], v[248:251], v[36:39]
	ds_read_b128 v[232:235], v185 offset:8768
	ds_read_b128 v[236:239], v187
	ds_read_b128 v[240:243], v185 offset:128
	ds_read_b128 v[248:251], v185 offset:4480
	s_waitcnt lgkmcnt(5)
	v_mfma_f32_16x16x32_bf16 v[44:47], v[220:223], v[224:227], v[44:47]
	s_waitcnt lgkmcnt(4)
	v_mfma_f32_16x16x32_bf16 v[40:43], v[220:223], v[228:231], v[40:43]
	s_waitcnt lgkmcnt(3)
	v_mfma_f32_16x16x32_bf16 v[36:39], v[220:223], v[232:235], v[36:39]
	ds_read_b128 v[220:223], v185 offset:8832
	ds_read_b128 v[224:227], v188
	ds_read_b128 v[228:231], v185 offset:192
	ds_read_b128 v[232:235], v185 offset:4544
	s_waitcnt lgkmcnt(5)
	v_mfma_f32_16x16x32_bf16 v[44:47], v[236:239], v[240:243], v[44:47]
	s_waitcnt lgkmcnt(4)
	v_mfma_f32_16x16x32_bf16 v[40:43], v[236:239], v[248:251], v[40:43]
	s_waitcnt lgkmcnt(3)
	v_mfma_f32_16x16x32_bf16 v[36:39], v[236:239], v[220:223], v[36:39]
	ds_read_b128 v[236:239], v185 offset:8896
	ds_read_b128 v[240:243], v184 offset:34816
	ds_read_b128 v[248:251], v185
	ds_read_b128 v[220:223], v185 offset:4352
	s_waitcnt lgkmcnt(5)
	v_mfma_f32_16x16x32_bf16 v[44:47], v[224:227], v[228:231], v[44:47]
	s_waitcnt lgkmcnt(4)
	v_mfma_f32_16x16x32_bf16 v[40:43], v[224:227], v[232:235], v[40:43]
	s_waitcnt lgkmcnt(3)
	v_mfma_f32_16x16x32_bf16 v[36:39], v[224:227], v[236:239], v[36:39]
	ds_read_b128 v[224:227], v185 offset:8704
	ds_read_b128 v[228:231], v186 offset:34816
	ds_read_b128 v[232:235], v185 offset:64
	ds_read_b128 v[236:239], v185 offset:4416
	s_waitcnt lgkmcnt(5)
	v_mfma_f32_16x16x32_bf16 v[92:95], v[240:243], v[248:251], v[92:95]
	s_waitcnt lgkmcnt(4)
	v_mfma_f32_16x16x32_bf16 v[88:91], v[240:243], v[220:223], v[88:91]
	s_waitcnt lgkmcnt(3)
	v_mfma_f32_16x16x32_bf16 v[80:83], v[240:243], v[224:227], v[80:83]
	ds_read_b128 v[240:243], v185 offset:8768
	ds_read_b128 v[248:251], v187 offset:34816
	ds_read_b128 v[220:223], v185 offset:128
	ds_read_b128 v[224:227], v185 offset:4480
	s_waitcnt lgkmcnt(5)
	v_mfma_f32_16x16x32_bf16 v[92:95], v[228:231], v[232:235], v[92:95]
	s_waitcnt lgkmcnt(4)
	v_mfma_f32_16x16x32_bf16 v[88:91], v[228:231], v[236:239], v[88:91]
	s_waitcnt lgkmcnt(3)
	v_mfma_f32_16x16x32_bf16 v[80:83], v[228:231], v[240:243], v[80:83]
	ds_read_b128 v[228:231], v185 offset:8832
	ds_read_b128 v[232:235], v188 offset:34816
	ds_read_b128 v[236:239], v185 offset:192
	ds_read_b128 v[240:243], v185 offset:4544
	s_waitcnt lgkmcnt(5)
	v_mfma_f32_16x16x32_bf16 v[92:95], v[248:251], v[220:223], v[92:95]
	s_waitcnt lgkmcnt(4)
	v_mfma_f32_16x16x32_bf16 v[88:91], v[248:251], v[224:227], v[88:91]
	s_waitcnt lgkmcnt(3)
	v_mfma_f32_16x16x32_bf16 v[80:83], v[248:251], v[228:231], v[80:83]
	ds_read_b128 v[248:251], v185 offset:8896
	s_waitcnt lgkmcnt(2)
	v_mfma_f32_16x16x32_bf16 v[92:95], v[232:235], v[236:239], v[92:95]
	s_waitcnt lgkmcnt(1)
	v_mfma_f32_16x16x32_bf16 v[88:91], v[232:235], v[240:243], v[88:91]
	s_waitcnt lgkmcnt(0)
	v_mfma_f32_16x16x32_bf16 v[80:83], v[232:235], v[248:251], v[80:83]
	v_mov_b32_e32 v104, v252
	s_and_saveexec_b64 s[0:1], s[44:45]
	s_cbranch_execz .LBB0_527
	v_mov_b32_e32 v106, s88
	ds_read_b32 v106, v106
	s_waitcnt vmcnt(21)
	v_max_f32_e32 v107, v203, v203
	s_cmp_eq_u32 s50, 1
	s_cselect_b32 s50, 0x820, 0
	s_add_i32 s50, s50, 0
	s_waitcnt lgkmcnt(0)
	v_max_f32_e32 v159, v106, v106
	v_max_f32_e32 v212, v159, v107
	s_waitcnt vmcnt(20)
	v_max_f32_e32 v107, v143, v143
	v_sub_f32_e32 v214, v106, v212
	v_max_f32_e32 v107, v159, v107
	v_sub_f32_e32 v159, v203, v212
	v_mul_f32_e32 v214, 0x3fb8aa3b, v214
	v_mul_f32_e32 v159, 0x3fb8aa3b, v159
	v_exp_f32_e32 v214, v214
	v_exp_f32_e32 v159, v159
	s_add_i32 s50, s50, 0x1a600
	v_lshl_add_u32 v213, v108, 2, s50
	v_mul_f32_e32 v214, 0x3d800000, v214
	ds_write2st64_b32 v213, v159, v214 offset1:2
	v_add_f32_e32 v159, v139, v212
	v_sub_f32_e32 v212, v141, v107
	v_mul_f32_e32 v159, 0xbfb8aa3b, v159
	v_mul_f32_e32 v212, 0x3fb8aa3b, v212
	v_exp_f32_e32 v159, v159
	v_exp_f32_e32 v212, v212
	ds_write2st64_b32 v213, v159, v212 offset0:4 offset1:6
	s_and_b64 exec, exec, s[10:11]
	s_cbranch_execz .LBB0_527
	v_sub_f32_e32 v106, v106, v107
	v_mul_f32_e32 v106, 0x3fb8aa3b, v106
	v_exp_f32_e32 v106, v106
	v_mov_b32_e32 v107, s50
	ds_write_b32 v107, v106 offset:2048
